# P4|P5 stays a global barrier (anti-dependency only) but its XCD leaders skip the L2 writeback when placement is consistent: nothing written in P4 is read by another XCD
# baseline (speedup 1.0000x reference)
; __device__ __forceinline__ unsigned xb_ld(unsigned* p)              { return __hip_atomic_load(p, __ATOMIC_RELAXED, __HIP_MEMORY_SCOPE_AGENT); }
; __device__ __forceinline__ unsigned xb_add(unsigned* p, unsigned v) { return __hip_atomic_fetch_add(p, v, __ATOMIC_RELAXED, __HIP_MEMORY_SCOPE_AGENT); }
; #define XB_SPIN(cond, bar) do { unsigned _sp = 0; while (cond) { __builtin_amdgcn_s_sleep(1); \
;     if ((++_sp & 255u) == 0u) { if (xb_ld(&(bar)[XB_TMO])) break; if (_sp > XB_SPIN_CAP) { atomicAdd(&(bar)[XB_TMO], 1u); break; } } } } while (0)
; __device__ __forceinline__ void xcd_barrier(const XcdBarrier& b) {
;     ...
;         const unsigned old = xb_add(&bar[XB_XSUB(b.x)], 1u);
;         const unsigned gen = old / nloc;
;         if (old + 1u == (gen + 1u) * nloc) {
;             __builtin_amdgcn_fence(__ATOMIC_RELEASE, "agent");
;             asm volatile("s_waitcnt vmcnt(0)" ::: "memory");
;             const unsigned og = xb_add(&bar[XB_TOP], 1u);
;             const unsigned tg = og / nx;
;             if (og + 1u == (tg + 1u) * nx) xb_add(&bar[XB_TOPGEN], 1u);
;             else XB_SPIN(xb_ld(&bar[XB_TOPGEN]) == tg, bar);
;             __builtin_amdgcn_fence(__ATOMIC_ACQUIRE, "agent");
;             xb_add(&bar[XB_XGEN(b.x)], 1u);
;             asm volatile("s_waitcnt vmcnt(0)" ::: "memory");
;         } else {
;             XB_SPIN(xb_ld(&bar[XB_XGEN(b.x)]) == gen, bar);
;             __builtin_amdgcn_fence(__ATOMIC_ACQUIRE, "agent");
.LBB0_643:
	s_andn2_saveexec_b64 s[6:7], s[6:7]
	s_cbranch_execz .LBB0_663
	s_mov_b64 s[6:7], exec
	v_readfirstlane_b32 s98, v238
	s_cmp_eq_u32 s98, 0
	s_cbranch_scc1 .Lnowb_45
	buffer_wbl2 sc1
.Lnowb_45:
	buffer_inv sc1
	s_waitcnt lgkmcnt(0)
	s_waitcnt vmcnt(0)
	v_mbcnt_lo_u32_b32 v1, s6, 0
	v_mbcnt_hi_u32_b32 v1, s7, v1
	v_cmp_eq_u32_e32 vcc, 0, v1
	s_and_saveexec_b64 s[8:9], vcc
	s_cbranch_execz .LBB0_646
	s_bcnt1_i32_b64 s6, s[6:7]
	v_mov_b32_e32 v2, 0x83000
	v_mov_b32_e32 v3, s6
	global_atomic_add v2, v2, v3, s[68:69] offset:1024 sc0
